# LN1: each wave normalises 16 consecutive rows instead of rows 2048 apart (page locality of loads and stores)
# baseline (speedup 1.0000x reference)
.LBB0_503:
	s_or_b64 exec, exec, s[6:7]
	s_waitcnt lgkmcnt(0)
	s_barrier
	v_mov_b32 v0, v214
	v_mov_b32 v1, v214
	v_readlane_b32 s0, v236, 34
	v_ashrrev_i32_e32 v1, 6, v1
	s_nop 0
	v_add_u32_e32 v32, s0, v1
	s_mov_b32 s0, 0x8000
	v_cmp_gt_i32_e32 vcc, s0, v32
	s_and_saveexec_b64 s[0:1], vcc
	v_readlane_b32 s24, v236, 40
	v_readlane_b32 s25, v236, 41
	s_cbranch_execz .LBB0_506
	v_lshlrev_b32_e32 v1, 6, v0
	v_readlane_b32 s8, v238, 20
	v_and_b32_e32 v2, 0xfc0, v1
	v_mov_b32_e32 v3, 0
	v_readlane_b32 s9, v238, 21
	v_readlane_b32 s10, v238, 22
	v_readlane_b32 s11, v238, 23
	v_ashrrev_i32_e32 v33, 31, v32
	v_lshl_add_u64 v[36:37], s[8:9], 0, v[2:3]
	v_lshl_add_u64 v[34:35], s[10:11], 0, v[2:3]
	s_cmpk_eq_i32 s24, 0x800
	s_cselect_b32 s12, 15, 11
	v_lshlrev_b64 v[2:3], s12, v[32:33]
	v_and_b32_e32 v0, 63, v0
	v_readlane_b32 s16, v238, 28
	v_readlane_b32 s17, v238, 29
	v_readlane_b32 s18, v238, 30
	v_readlane_b32 s19, v238, 31
	v_readlane_b32 s20, v238, 32
	v_readlane_b32 s21, v238, 33
	v_lshl_or_b32 v2, v0, 5, v2
	v_readlane_b32 s18, v236, 48
	v_readlane_b32 s16, v236, 46
	v_readlane_b32 s20, v236, 44
	v_lshl_add_u64 v[0:1], s[94:95], 0, v[2:3]
	s_mov_b64 s[6:7], 0x108e8000
	s_ashr_i32 s25, s24, 31
	v_readlane_b32 s19, v236, 49
	v_readlane_b32 s17, v236, 47
	v_readlane_b32 s21, v236, 45
	v_lshl_add_u64 v[38:39], v[0:1], 0, s[6:7]
	s_lshl_b64 s[6:7], s[24:25], 11
	s_cmpk_eq_i32 s24, 0x800
	s_cselect_b64 s[6:7], 0x800, s[6:7]
	s_mov_b64 s[8:9], 0
	v_mov_b32_e32 v33, 0x3a800000
	v_mov_b32_e32 v40, 0x3727c5ac
	v_readlane_b32 s12, v238, 24
	v_readlane_b32 s13, v238, 25
	v_readlane_b32 s14, v238, 26
	v_readlane_b32 s15, v238, 27
	v_readlane_b32 s22, v238, 34
	v_readlane_b32 s23, v238, 35
